# v21: SWA-layer rope items (256, one per wave on 32 CUs) split 4-way over 1024 waves
# speedup vs baseline: 1.0166x; 1.0118x over previous
; #define PHASE_IDS() int lane_; asm volatile("v_mbcnt_lo_u32_b32 %0, -1, 0\n\tv_mbcnt_hi_u32_b32 %0, -1, %0" : "=v"(lane_)); const int lane = lane_, wave = wave_s; int gw_ = (int)blockIdx.x * NWAVES + wave; asm volatile("" : "+s"(gw_)); const int gw = gw_; const int x32 = (lane ^ 32) << 2; (void)gw; (void)lane; (void)x32
; DI void rope_phase(bf16* qb, unsigned char* kfb, int nkv, const float* gains, bool do_kmean, bf16* kmean, int NGW, const int wave_s) {
;     const int nslots = nkv;
;     PHASE_IDS();
;     const int sub = lane >> 3, j = lane & 7;
;     float invf[8];
; #pragma unroll
;     for (int t = 0; t < 8; ++t) invf[t] = exp2f(-(float)(8 * (j & 3) + t) * (13.287712379549449f / 32.f));
;     for (int id = gw; id < NB * 16 * nslots; id += NGW) {
;         const int slot = 16 + id % nslots, bn = id / nslots, b = bn >> 4, n = bn & 15;
.LBB0_397:
	s_mov_b64 s[14:15], s[0:1]
	v_readlane_b32 s22, v242, 4
	s_lshl_b32 s23, s40, 7
	s_mov_b32 s98, 0
	s_mov_b32 s99, -8
	s_cmp_lg_u32 s40, 2
	s_cbranch_scc1 .Lrope_full
	s_and_b32 s98, s22, 3
	s_lshl_b32 s98, s98, 6
	s_lshr_b32 s22, s22, 2
	s_mov_b32 s99, 16
.Lrope_full:
	v_mbcnt_lo_u32_b32 v2, -1, 0
	v_mbcnt_hi_u32_b32 v2, -1, v2
	s_cmp_ge_i32 s22, s23
	s_cbranch_scc1 .LBB0_430
	v_lshlrev_b32_e32 v4, 3, v2
	v_and_b32_e32 v3, 24, v4
	v_cvt_f32_ubyte0_e32 v5, v3
	v_mul_f32_e32 v6, 0xbed49a78, v5
	v_cmp_gt_f32_e32 vcc, s91, v6
	v_lshlrev_b32_e32 v0, 2, v2
	s_load_dwordx2 s[12:13], s[10:11], 0x0
	s_nop 0
	s_load_dwordx2 s[14:15], s[14:15], 0x90
	v_cndmask_b32_e32 v6, 0, v206, vcc
	v_fmac_f32_e32 v6, 0xbed49a78, v5
	v_exp_f32_e32 v5, v6
	v_cndmask_b32_e32 v6, 0, v207, vcc
	v_xor_b32_e32 v219, 0x80, v0
	v_lshlrev_b32_e32 v0, 9, v2
	v_ldexp_f32 v211, v5, v6
	v_or_b32_e32 v5, 1, v3
	v_cvt_f32_ubyte0_e32 v5, v5
	v_mul_f32_e32 v6, 0xbed49a78, v5
	v_cmp_gt_f32_e32 vcc, s91, v6
	v_and_b32_e32 v0, 0xc00, v0
	v_ashrrev_i32_e32 v210, 3, v2
	v_cndmask_b32_e32 v6, 0, v206, vcc
	v_fmac_f32_e32 v6, 0xbed49a78, v5
	v_exp_f32_e32 v5, v6
	v_cndmask_b32_e32 v6, 0, v207, vcc
	s_abs_i32 s25, s40
	s_ashr_i32 s24, s40, 31
	v_ldexp_f32 v212, v5, v6
	v_or_b32_e32 v5, 2, v3
	v_cvt_f32_ubyte0_e32 v5, v5
	v_mul_f32_e32 v6, 0xbed49a78, v5
	v_cmp_gt_f32_e32 vcc, s91, v6
	s_nop 1
	v_cndmask_b32_e32 v6, 0, v206, vcc
	v_fmac_f32_e32 v6, 0xbed49a78, v5
	v_exp_f32_e32 v5, v6
	v_cndmask_b32_e32 v6, 0, v207, vcc
	v_ldexp_f32 v213, v5, v6
	v_or_b32_e32 v5, 3, v3
	v_cvt_f32_ubyte0_e32 v5, v5
	v_mul_f32_e32 v6, 0xbed49a78, v5
	v_cmp_gt_f32_e32 vcc, s91, v6
	s_nop 1
	v_cndmask_b32_e32 v6, 0, v206, vcc
	v_fmac_f32_e32 v6, 0xbed49a78, v5
	v_exp_f32_e32 v5, v6
	v_cndmask_b32_e32 v6, 0, v207, vcc
	v_ldexp_f32 v214, v5, v6
	v_or_b32_e32 v5, 4, v3
	v_cvt_f32_ubyte0_e32 v5, v5
	v_mul_f32_e32 v6, 0xbed49a78, v5
	v_cmp_gt_f32_e32 vcc, s91, v6
	s_nop 1
	v_cndmask_b32_e32 v6, 0, v206, vcc
	v_fmac_f32_e32 v6, 0xbed49a78, v5
	v_exp_f32_e32 v5, v6
	v_cndmask_b32_e32 v6, 0, v207, vcc
	v_ldexp_f32 v215, v5, v6
	v_or_b32_e32 v5, 5, v3
	v_cvt_f32_ubyte0_e32 v5, v5
	v_mul_f32_e32 v6, 0xbed49a78, v5
	v_cmp_gt_f32_e32 vcc, s91, v6
	s_nop 1
	v_cndmask_b32_e32 v6, 0, v206, vcc
	v_fmac_f32_e32 v6, 0xbed49a78, v5
	v_exp_f32_e32 v5, v6
	v_cndmask_b32_e32 v6, 0, v207, vcc
	v_ldexp_f32 v216, v5, v6
	v_or_b32_e32 v5, 6, v3
	v_cvt_f32_ubyte0_e32 v5, v5
	v_mul_f32_e32 v6, 0xbed49a78, v5
	v_cmp_gt_f32_e32 vcc, s91, v6
	v_or_b32_e32 v3, 7, v3
	v_cvt_f32_ubyte0_e32 v3, v3
	v_cndmask_b32_e32 v6, 0, v206, vcc
	v_fmac_f32_e32 v6, 0xbed49a78, v5
	v_exp_f32_e32 v5, v6
	v_cndmask_b32_e32 v6, 0, v207, vcc
	v_ldexp_f32 v217, v5, v6
	v_mul_f32_e32 v5, 0xbed49a78, v3
	v_cmp_gt_f32_e32 vcc, s91, v5
	s_waitcnt lgkmcnt(0)
	v_lshl_add_u64 v[6:7], s[8:9], 0, v[0:1]
	v_lshlrev_b32_e32 v0, 5, v2
	v_cndmask_b32_e32 v5, 0, v206, vcc
	v_fmac_f32_e32 v5, 0xbed49a78, v3
	v_exp_f32_e32 v3, v5
	v_cndmask_b32_e32 v5, 0, v207, vcc
	v_and_b32_e32 v0, 32, v0
	s_mov_b64 s[8:9], 0x12800000
	v_ldexp_f32 v218, v3, v5
	v_and_b32_e32 v3, 7, v2
	v_lshlrev_b32_e32 v5, 1, v210
	v_and_or_b32 v221, v5, 8, v0
	v_lshlrev_b32_e32 v0, 4, v3
	v_mov_b32_e32 v5, v1
	v_lshlrev_b32_e32 v220, 3, v3
	v_lshl_add_u64 v[42:43], v[6:7], 0, s[8:9]
	v_lshl_add_u64 v[44:45], s[4:5], 0, v[0:1]
	v_cmp_gt_u32_e64 s[10:11], 4, v3
	v_cmp_gt_u32_e64 s[4:5], 8, v2
	v_lshl_add_u64 v[2:3], v[4:5], 1, s[14:15]
	s_mov_b64 s[8:9], 0x100000
	v_lshl_add_u64 v[46:47], v[2:3], 0, s[8:9]
	v_lshrrev_b32_e32 v2, 1, v210
	v_and_b32_e32 v0, 19, v210
	v_and_b32_e32 v2, 4, v2
	v_or3_b32 v0, v0, v2, v221
	v_lshlrev_b32_e32 v0, 4, v0
	v_lshl_add_u64 v[48:49], v[42:43], 0, v[0:1]
	v_cvt_f32_u32_e32 v0, s25
	s_sub_i32 s8, 0, s25
	v_or_b32_e32 v222, v221, v2
	s_xor_b64 s[14:15], s[6:7], -1
	v_rcp_iflag_f32_e32 v0, v0
	s_nop 0
	v_mul_f32_e32 v0, 0x4f7ffffe, v0
	v_cvt_u32_f32_e32 v0, v0
	s_nop 0
	v_readfirstlane_b32 s9, v0
	s_mul_i32 s8, s8, s9
	s_mul_hi_u32 s8, s9, s8
	s_add_i32 s26, s9, s8
	s_branch .LBB0_401

; __device__ __forceinline__ int pi32(int m) { return (m & 19) | ((m & 4) << 1) | ((m & 8) >> 1); }
; DI void rope_phase(bf16* qb, unsigned char* kfb, int nkv, const float* gains, bool do_kmean, bf16* kmean, int NGW, const int wave_s) {
;     ...
;     for (int id = gw; id < NB * 16 * nslots; id += NGW) {
;         const int slot = 16 + id % nslots, bn = id / nslots, b = bn >> 4, n = bn & 15;
;         float g[8];
; #pragma unroll
;         for (int t = 0; t < 8; ++t) g[t] = gains[(slot < 16 ? 0 : 64) + 8 * j + t];
;         float ksum[8];
; #pragma unroll
;         for (int t = 0; t < 8; ++t) ksum[t] = 0.f;
;         for (int itb = 0; itb < 32; itb += 8) {
;             v4u rawv[8]; bf16* ptrv[8];
; #pragma unroll
;             for (int u = 0; u < 8; ++u) { const int tok = n * 256 + (itb + u) * 8 + sub;
;                 ptrv[u] = (slot < 16) ? qb + (size_t)(b * SEQ + tok) * 1024 + slot * 64 + 8 * j
;                                       : (bf16*)(kfb + ((size_t)((b * nkv + (slot - 16)) * 128 + (tok >> 5)) << 12) + (j >> 1) * 1024 + ((j & 1) * 32 + pg8::pi32(tok & 31)) * 16);
;                 rawv[u] = *(const v4u*)ptrv[u]; }
.LBB0_401:
	s_abs_i32 s7, s22
	s_mul_hi_u32 s8, s7, s26
	s_mul_i32 s9, s8, s25
	s_ashr_i32 s6, s22, 31
	s_sub_i32 s7, s7, s9
	s_xor_b32 s6, s6, s24
	s_add_i32 s9, s8, 1
	s_sub_i32 s16, s7, s25
	s_cmp_ge_u32 s7, s25
	s_cselect_b32 s8, s9, s8
	s_cselect_b32 s7, s16, s7
	s_add_i32 s9, s8, 1
	s_cmp_ge_u32 s7, s25
	s_cselect_b32 s7, s9, s8
	s_xor_b32 s7, s7, s6
	s_sub_i32 s27, s7, s6
	s_mul_i32 s6, s27, s40
	s_sub_i32 s28, s22, s6
	s_ashr_i32 s18, s27, 4
	s_cmp_lt_i32 s28, 0
	s_cselect_b64 s[6:7], -1, 0
	s_cmp_gt_i32 s28, -1
	s_cselect_b64 s[16:17], -1, 0
	s_and_b64 s[8:9], s[6:7], exec
	s_cselect_b32 s8, 0, 64
	v_or_b32_e32 v0, s8, v220
	v_lshlrev_b32_e32 v0, 2, v0
	global_load_dwordx4 v[2:5], v0, s[12:13] offset:16
	global_load_dwordx4 v[6:9], v0, s[12:13]
	s_lshl_b32 s8, s18, s41
	s_add_i32 s8, s8, s28
	s_lshl_b32 s30, s8, 7
	s_lshl_b32 s8, s28, 6
	s_ashr_i32 s9, s8, 31
	s_and_b32 s29, s27, 15
	s_lshl_b32 s31, s18, 12
	v_lshl_add_u64 v[10:11], s[8:9], 1, v[44:45]
	s_mov_b64 s[8:9], 0xe800800
	v_lshl_add_u64 v[50:51], v[10:11], 0, s[8:9]
	s_and_b64 s[8:9], s[6:7], exec
	v_mov_b32_e32 v66, 0
	v_lshl_add_u32 v223, s29, 8, v210
	v_add_u32_e32 v223, s98, v223
	v_cndmask_b32_e64 v53, v49, v51, s[6:7]
	s_cselect_b32 s34, 11, 12
	v_cndmask_b32_e64 v52, v48, v50, s[6:7]
	s_mov_b32 s35, s99
	v_mov_b32_e32 v67, v66
	v_mov_b32_e32 v70, v66
	v_mov_b32_e32 v71, v66
	v_mov_b32_e32 v72, v66
	v_mov_b32_e32 v73, v66
	v_mov_b32_e32 v68, v66
	v_mov_b32_e32 v69, v66
	s_branch .LBB0_403
